# P5 tile start: Q and rope loads of all four n-tiles issued up front into spare registers (one round trip)
# baseline (speedup 1.0000x reference)
.LBB0_644:
	s_or_b64 exec, exec, s[40:41]
	s_waitcnt lgkmcnt(0)
	s_barrier
	ds_read_b32 v0, v226
	s_movk_i32 s2, 0x3ff
	s_mov_b64 s[40:41], -1
	s_waitcnt lgkmcnt(0)
	v_cmp_lt_i32_e32 vcc, s2, v0
	v_readfirstlane_b32 s26, v0
	s_cbranch_vccnz .LBB0_639
	s_ashr_i32 s64, s26, 2
	v_mov_b32_e32 v10, v218
	s_sub_i32 s69, 0xff, s64
	s_and_b32 s45, s26, 1
	s_lshl_b32 s2, s26, 13
	v_ashrrev_i32_e32 v0, 2, v10
	v_and_b32_e32 v240, -16, v0
	s_and_b32 s84, s2, 0x4000
	s_lshl_b32 s2, s69, 6
	s_lshl_b32 s3, s45, 2
	v_add_u32_e32 v198, s2, v240
	v_and_or_b32 v214, v10, 3, s3
	s_add_i32 s2, s84, s2
	s_mov_b32 s3, s85
	v_ashrrev_i32_e32 v1, 31, v0
	v_lshl_add_u64 v[2:3], s[2:3], 0, v[0:1]
	v_lshlrev_b32_e32 v1, 3, v10
	v_and_b32_e32 v128, 24, v1
	v_ashrrev_i32_e32 v199, 31, v198
	v_lshlrev_b64 v[2:3], 6, v[2:3]
	v_lshl_or_b32 v11, v0, 5, v128
	v_lshl_add_u64 v[200:201], v[198:199], 0, s[84:85]
	v_bfe_u32 v0, v10, 2, 2
	v_lshl_add_u64 v[2:3], s[56:57], 0, v[2:3]
	s_lshl_b32 s2, s45, 5
	v_or_b32_e32 v200, v200, v0
	v_mov_b64_e32 v[0:1], s[52:53]
	v_lshl_add_u64 v[2:3], v[2:3], 0, s[2:3]
	v_mad_u64_u32 v[18:19], s[2:3], v200, s10, v[0:1]
	v_bfe_u32 v241, v10, 4, 2
	v_lshl_add_u64 v[2:3], v[2:3], 0, v[128:129]
	v_mad_i32_i24 v19, v201, s10, v19
	v_lshlrev_b32_e32 v128, 7, v214
	v_lshl_add_u64 v[0:1], v[18:19], 0, v[128:129]
	v_lshlrev_b32_e32 v202, 4, v241
	v_mov_b32_e32 v203, v129
	v_lshl_add_u64 v[4:5], v[0:1], 0, v[202:203]
	global_load_dwordx2 v[2:3], v[2:3], off
	s_mov_b64 s[2:3], 0x6000
	v_lshlrev_b64 v[124:125], 6, v[200:201]
	v_lshl_add_u64 v[124:125], s[54:55], 0, v[124:125]
	global_load_dwordx4 v[40:43], v[4:5], off offset:2112
	global_load_dwordx4 v[44:47], v[0:1], off offset:2048
	global_load_dwordx4 v[48:51], v[0:1], off offset:2064
	global_load_dwordx4 v[52:55], v[124:125], off offset:48
	global_load_dwordx4 v[56:59], v[124:125], off offset:16
	global_load_dwordx4 v[60:63], v[124:125], off offset:32
	global_load_dwordx4 v[64:67], v[124:125], off
	global_load_dwordx4 v[68:71], v[4:5], off offset:2048
	v_lshl_add_u64 v[36:37], v[0:1], 0, s[2:3]
	v_lshl_add_u64 v[38:39], v[4:5], 0, s[2:3]
	global_load_dwordx4 v[76:79], v[38:39], off offset:2112
	global_load_dwordx4 v[80:83], v[36:37], off offset:2048
	global_load_dwordx4 v[84:87], v[36:37], off offset:2064
	global_load_dwordx4 v[88:91], v[124:125], off offset:304
	global_load_dwordx4 v[92:95], v[124:125], off offset:272
	global_load_dwordx4 v[96:99], v[124:125], off offset:288
	global_load_dwordx4 v[116:119], v[124:125], off offset:256
	global_load_dwordx4 v[120:123], v[38:39], off offset:2048
	v_lshl_add_u64 v[36:37], v[36:37], 0, s[2:3]
	v_lshl_add_u64 v[38:39], v[38:39], 0, s[2:3]
	global_load_dwordx4 v[130:133], v[38:39], off offset:2112
	global_load_dwordx4 v[134:137], v[36:37], off offset:2048
	global_load_dwordx4 v[138:141], v[36:37], off offset:2064
	global_load_dwordx4 v[142:145], v[124:125], off offset:560
	global_load_dwordx4 v[146:149], v[124:125], off offset:528
	global_load_dwordx4 v[150:153], v[124:125], off offset:544
	global_load_dwordx4 v[154:157], v[124:125], off offset:512
	global_load_dwordx4 v[158:161], v[38:39], off offset:2048
	v_lshl_add_u64 v[36:37], v[36:37], 0, s[2:3]
	v_lshl_add_u64 v[38:39], v[38:39], 0, s[2:3]
	global_load_dwordx4 v[162:165], v[38:39], off offset:2112
	global_load_dwordx4 v[166:169], v[36:37], off offset:2048
	global_load_dwordx4 v[170:173], v[36:37], off offset:2064
	global_load_dwordx4 v[174:177], v[124:125], off offset:816
	global_load_dwordx4 v[178:181], v[124:125], off offset:784
	global_load_dwordx4 v[182:185], v[124:125], off offset:800
	global_load_dwordx4 v[186:189], v[124:125], off offset:768
	global_load_dwordx4 v[190:193], v[38:39], off offset:2048
	v_and_b32_e32 v12, 15, v10
	v_and_b32_e32 v10, 0xfffffc0, v10
	v_mul_lo_u32 v199, v10, s31
	v_add_u32_e32 v10, 0x11000, v11
	v_mul_u32_u24_e32 v14, 0x90, v12
	v_cmp_gt_u32_e64 s[42:43], 2, v241
	v_cmp_eq_u32_e32 vcc, 0, v241
	v_add3_u32 v22, v199, v14, v202
	s_waitcnt vmcnt(32)
	ds_write_b64 v10, v[2:3]
	s_waitcnt vmcnt(24)
	v_and_b32_e32 v3, 0xffff0000, v40
	v_lshlrev_b32_e32 v2, 16, v40
	v_and_b32_e32 v11, 0xffff0000, v41
	v_lshlrev_b32_e32 v10, 16, v41
	v_and_b32_e32 v7, 0xffff0000, v42
	v_lshlrev_b32_e32 v6, 16, v42
	v_and_b32_e32 v13, 0xffff0000, v43
	v_lshlrev_b32_e32 v12, 16, v43
	v_pk_mul_f32 v[2:3], v[2:3], s[30:31] op_sel_hi:[1,0]
	v_pk_mul_f32 v[8:9], v[10:11], s[30:31] op_sel_hi:[1,0]
	v_pk_mul_f32 v[10:11], v[6:7], s[30:31] op_sel_hi:[1,0]
	v_pk_mul_f32 v[12:13], v[12:13], s[30:31] op_sel_hi:[1,0]
	v_cvt_pk_bf16_f32 v6, v2, v3
	v_cvt_pk_bf16_f32 v7, v8, v9
	v_cvt_pk_bf16_f32 v8, v10, v11
	v_cvt_pk_bf16_f32 v9, v12, v13
	ds_write_b128 v22, v[6:9] offset:32832
	s_and_saveexec_b64 s[2:3], s[42:43]
	s_xor_b64 s[40:41], exec, s[2:3]
	s_cbranch_execz .LBB0_647
	v_lshlrev_b64 v[0:1], 6, v[200:201]
	v_lshl_add_u64 v[0:1], s[54:55], 0, v[0:1]
	v_and_b32_e32 v21, 0xffff0000, v44
	v_and_b32_e32 v33, 0xffff0000, v48
	v_lshlrev_b32_e32 v32, 16, v48
	v_lshlrev_b32_e32 v20, 16, v44
	v_pk_mul_f32 v[0:1], v[60:61], v[32:33]
	v_lshlrev_b32_e32 v10, 16, v49
	v_pk_fma_f32 v[0:1], v[64:65], v[20:21], v[0:1] neg_lo:[0,0,1] neg_hi:[0,0,1]
	v_pk_mul_f32 v[28:29], v[64:65], v[32:33]
	s_nop 0
	v_pk_fma_f32 v[20:21], v[60:61], v[20:21], v[28:29]
	s_nop 0
	v_cndmask_b32_e32 v1, v21, v1, vcc
	v_cndmask_b32_e32 v0, v20, v0, vcc
	v_and_b32_e32 v21, 0xffff0000, v45
	v_lshlrev_b32_e32 v20, 16, v45
	v_and_b32_e32 v11, 0xffff0000, v49
	v_pk_mul_f32 v[14:15], v[62:63], v[10:11]
	v_pk_mul_f32 v[0:1], v[0:1], s[30:31] op_sel_hi:[1,0]
	v_pk_fma_f32 v[14:15], v[66:67], v[20:21], v[14:15] neg_lo:[0,0,1] neg_hi:[0,0,1]
	v_pk_mul_f32 v[20:21], v[62:63], v[20:21]
	v_cvt_pk_bf16_f32 v0, v0, v1
	v_pk_fma_f32 v[10:11], v[66:67], v[10:11], v[20:21]
	s_nop 0
	v_cndmask_b32_e32 v11, v11, v15, vcc
	v_cndmask_b32_e32 v10, v10, v14, vcc
	v_pk_mul_f32 v[10:11], v[10:11], s[30:31] op_sel_hi:[1,0]
	v_and_b32_e32 v15, 0xffff0000, v50
	v_cvt_pk_bf16_f32 v1, v10, v11
	v_and_b32_e32 v11, 0xffff0000, v46
	v_lshlrev_b32_e32 v10, 16, v46
	v_lshlrev_b32_e32 v14, 16, v50
	v_pk_mul_f32 v[20:21], v[52:53], v[14:15]
	v_pk_mul_f32 v[6:7], v[52:53], v[10:11]
	v_pk_fma_f32 v[20:21], v[56:57], v[10:11], v[20:21] neg_lo:[0,0,1] neg_hi:[0,0,1]
	v_pk_fma_f32 v[2:3], v[56:57], v[14:15], v[6:7]
	v_lshlrev_b32_e32 v7, 16, v51
	v_cndmask_b32_e32 v3, v3, v21, vcc
	v_cndmask_b32_e32 v2, v2, v20, vcc
	v_lshlrev_b32_e32 v6, 16, v47
	v_mov_b32_e32 v10, v58
	v_mov_b32_e32 v11, v54
	v_pk_mul_f32 v[2:3], v[2:3], s[30:31] op_sel_hi:[1,0]
	v_pk_mul_f32 v[10:11], v[10:11], v[6:7]
	v_cvt_pk_bf16_f32 v2, v2, v3
	v_sub_f32_e32 v3, v10, v11
	v_mov_b32_e32 v10, v54
	v_mov_b32_e32 v11, v58
	v_pk_mul_f32 v[6:7], v[10:11], v[6:7]
	v_mov_b32_e32 v8, v59
	v_add_f32_e32 v4, v7, v6
	v_cndmask_b32_e32 v3, v4, v3, vcc
	v_and_b32_e32 v7, 0xffff0000, v51
	v_and_b32_e32 v6, 0xffff0000, v47
	v_mov_b32_e32 v4, v55
	v_mul_f32_e32 v3, 0x3e38aa3b, v3
	v_mov_b32_e32 v9, v55
	v_pk_mul_f32 v[10:11], v[8:9], v[6:7]
	v_mov_b32_e32 v5, v59
	v_pk_mul_f32 v[4:5], v[4:5], v[6:7]
	v_cvt_pk_bf16_f32 v3, v3, s0
	v_sub_f32_e32 v8, v10, v11
	v_add_f32_e32 v4, v5, v4
	v_perm_b32 v3, 0, v3, v238
	v_cndmask_b32_e32 v6, v4, v8, vcc
.LBB0_647:
	s_andn2_saveexec_b64 s[40:41], s[40:41]
	s_cbranch_execz .LBB0_649
	v_and_b32_e32 v1, 0xffff0000, v68
	v_lshlrev_b32_e32 v0, 16, v68
	v_and_b32_e32 v7, 0xffff0000, v69
	v_lshlrev_b32_e32 v6, 16, v69
	v_pk_mul_f32 v[0:1], v[0:1], s[30:31] op_sel_hi:[1,0]
	v_pk_mul_f32 v[2:3], v[6:7], s[30:31] op_sel_hi:[1,0]
	v_cvt_pk_bf16_f32 v0, v0, v1
	v_cvt_pk_bf16_f32 v1, v2, v3
	v_and_b32_e32 v3, 0xffff0000, v70
	v_lshlrev_b32_e32 v2, 16, v70
	v_pk_mul_f32 v[2:3], v[2:3], s[30:31] op_sel_hi:[1,0]
	v_and_b32_e32 v6, 0xffff0000, v71
	v_cvt_pk_bf16_f32 v2, v2, v3
	v_lshlrev_b32_e32 v3, 16, v71
	v_mul_f32_e32 v3, 0x3e38aa3b, v3
	v_cvt_pk_bf16_f32 v3, v3, s0
	v_perm_b32 v3, 0, v3, v238
.LBB0_649:
	s_or_b64 exec, exec, s[40:41]
	v_mul_f32_e32 v5, 0x3e38aa3b, v6
	v_lshlrev_b32_e32 v203, 6, v214
	v_cvt_pk_bf16_f32 v5, v5, s0
	s_mov_b64 s[2:3], 0x6000
	v_lshlrev_b32_e32 v4, 3, v241
	v_perm_b32 v3, v5, v3, s12
	v_lshl_add_u64 v[20:21], v[18:19], 0, s[2:3]
	v_lshlrev_b32_e32 v128, 1, v203
	ds_write_b128 v22, v[0:3] offset:32768
	v_lshl_add_u64 v[0:1], v[20:21], 0, v[128:129]
	v_lshlrev_b32_e32 v18, 1, v4
	v_mov_b32_e32 v19, v129
	v_lshl_add_u64 v[4:5], v[0:1], 0, v[18:19]
	v_or_b32_e32 v204, 4, v200
	v_mov_b32_e32 v205, v201
	s_waitcnt vmcnt(16)
	v_and_b32_e32 v3, 0xffff0000, v76
	v_lshlrev_b32_e32 v2, 16, v76
	v_pk_mul_f32 v[2:3], v[2:3], s[30:31] op_sel_hi:[1,0]
	s_nop 0
	v_cvt_pk_bf16_f32 v6, v2, v3
	v_and_b32_e32 v3, 0xffff0000, v77
	v_lshlrev_b32_e32 v2, 16, v77
	v_pk_mul_f32 v[2:3], v[2:3], s[30:31] op_sel_hi:[1,0]
	s_nop 0
	v_cvt_pk_bf16_f32 v7, v2, v3
	v_and_b32_e32 v3, 0xffff0000, v78
	v_lshlrev_b32_e32 v2, 16, v78
	v_pk_mul_f32 v[2:3], v[2:3], s[30:31] op_sel_hi:[1,0]
	s_nop 0
	v_cvt_pk_bf16_f32 v8, v2, v3
	v_and_b32_e32 v3, 0xffff0000, v79
	v_lshlrev_b32_e32 v2, 16, v79
	v_pk_mul_f32 v[2:3], v[2:3], s[30:31] op_sel_hi:[1,0]
	s_nop 0
	v_cvt_pk_bf16_f32 v9, v2, v3
	ds_write_b128 v22, v[6:9] offset:35136
	s_and_saveexec_b64 s[2:3], s[42:43]
	s_xor_b64 s[40:41], exec, s[2:3]
	s_cbranch_execz .LBB0_651
	v_lshlrev_b64 v[0:1], 6, v[204:205]
	v_lshl_add_u64 v[0:1], s[54:55], 0, v[0:1]
	v_and_b32_e32 v33, 0xffff0000, v80
	v_and_b32_e32 v35, 0xffff0000, v84
	v_lshlrev_b32_e32 v34, 16, v84
	v_lshlrev_b32_e32 v32, 16, v80
	v_pk_mul_f32 v[0:1], v[96:97], v[34:35]
	v_lshlrev_b32_e32 v10, 16, v85
	v_pk_fma_f32 v[0:1], v[116:117], v[32:33], v[0:1] neg_lo:[0,0,1] neg_hi:[0,0,1]
	v_pk_mul_f32 v[28:29], v[116:117], v[34:35]
	s_nop 0
	v_pk_fma_f32 v[24:25], v[96:97], v[32:33], v[28:29]
	s_nop 0
	v_cndmask_b32_e32 v1, v25, v1, vcc
	v_cndmask_b32_e32 v0, v24, v0, vcc
	v_and_b32_e32 v25, 0xffff0000, v81
	v_lshlrev_b32_e32 v24, 16, v81
	v_and_b32_e32 v11, 0xffff0000, v85
	v_pk_mul_f32 v[14:15], v[98:99], v[10:11]
	v_pk_mul_f32 v[0:1], v[0:1], s[30:31] op_sel_hi:[1,0]
	v_pk_fma_f32 v[14:15], v[118:119], v[24:25], v[14:15] neg_lo:[0,0,1] neg_hi:[0,0,1]
	v_pk_mul_f32 v[24:25], v[98:99], v[24:25]
	v_cvt_pk_bf16_f32 v0, v0, v1
	v_pk_fma_f32 v[10:11], v[118:119], v[10:11], v[24:25]
	s_nop 0
	v_cndmask_b32_e32 v11, v11, v15, vcc
	v_cndmask_b32_e32 v10, v10, v14, vcc
	v_pk_mul_f32 v[10:11], v[10:11], s[30:31] op_sel_hi:[1,0]
	v_and_b32_e32 v15, 0xffff0000, v86
	v_cvt_pk_bf16_f32 v1, v10, v11
	v_and_b32_e32 v11, 0xffff0000, v82
	v_lshlrev_b32_e32 v10, 16, v82
	v_lshlrev_b32_e32 v14, 16, v86
	v_pk_mul_f32 v[24:25], v[88:89], v[14:15]
	v_pk_mul_f32 v[6:7], v[88:89], v[10:11]
	v_pk_fma_f32 v[24:25], v[92:93], v[10:11], v[24:25] neg_lo:[0,0,1] neg_hi:[0,0,1]
	v_pk_fma_f32 v[2:3], v[92:93], v[14:15], v[6:7]
	v_lshlrev_b32_e32 v7, 16, v87
	v_cndmask_b32_e32 v3, v3, v25, vcc
	v_cndmask_b32_e32 v2, v2, v24, vcc
	v_lshlrev_b32_e32 v6, 16, v83
	v_mov_b32_e32 v10, v94
	v_mov_b32_e32 v11, v90
	v_pk_mul_f32 v[2:3], v[2:3], s[30:31] op_sel_hi:[1,0]
	v_pk_mul_f32 v[10:11], v[10:11], v[6:7]
	v_cvt_pk_bf16_f32 v2, v2, v3
	v_sub_f32_e32 v3, v10, v11
	v_mov_b32_e32 v10, v90
	v_mov_b32_e32 v11, v94
	v_pk_mul_f32 v[6:7], v[10:11], v[6:7]
	v_mov_b32_e32 v8, v95
	v_add_f32_e32 v4, v7, v6
	v_cndmask_b32_e32 v3, v4, v3, vcc
	v_and_b32_e32 v7, 0xffff0000, v87
	v_and_b32_e32 v6, 0xffff0000, v83
	v_mov_b32_e32 v4, v91
	v_mul_f32_e32 v3, 0x3e38aa3b, v3
	v_mov_b32_e32 v9, v91
	v_pk_mul_f32 v[10:11], v[8:9], v[6:7]
	v_mov_b32_e32 v5, v95
	v_pk_mul_f32 v[4:5], v[4:5], v[6:7]
	v_cvt_pk_bf16_f32 v3, v3, s0
	v_sub_f32_e32 v8, v10, v11
	v_add_f32_e32 v4, v5, v4
	v_perm_b32 v3, 0, v3, v238
	v_cndmask_b32_e32 v6, v4, v8, vcc
.LBB0_651:
	s_andn2_saveexec_b64 s[40:41], s[40:41]
	s_cbranch_execz .LBB0_653
	v_and_b32_e32 v1, 0xffff0000, v120
	v_lshlrev_b32_e32 v0, 16, v120
	v_and_b32_e32 v7, 0xffff0000, v121
	v_lshlrev_b32_e32 v6, 16, v121
	v_pk_mul_f32 v[0:1], v[0:1], s[30:31] op_sel_hi:[1,0]
	v_pk_mul_f32 v[2:3], v[6:7], s[30:31] op_sel_hi:[1,0]
	v_cvt_pk_bf16_f32 v0, v0, v1
	v_cvt_pk_bf16_f32 v1, v2, v3
	v_and_b32_e32 v3, 0xffff0000, v122
	v_lshlrev_b32_e32 v2, 16, v122
	v_pk_mul_f32 v[2:3], v[2:3], s[30:31] op_sel_hi:[1,0]
	v_and_b32_e32 v6, 0xffff0000, v123
	v_cvt_pk_bf16_f32 v2, v2, v3
	v_lshlrev_b32_e32 v3, 16, v123
	v_mul_f32_e32 v3, 0x3e38aa3b, v3
	v_cvt_pk_bf16_f32 v3, v3, s0
	v_perm_b32 v3, 0, v3, v238
.LBB0_653:
	s_or_b64 exec, exec, s[40:41]
	v_mul_f32_e32 v4, 0x3e38aa3b, v6
	v_cvt_pk_bf16_f32 v4, v4, s0
	s_mov_b64 s[2:3], 0x6000
	v_perm_b32 v3, v4, v3, s12
	v_lshl_add_u64 v[20:21], v[20:21], 0, s[2:3]
	ds_write_b128 v22, v[0:3] offset:35072
	v_lshl_add_u64 v[0:1], v[20:21], 0, v[128:129]
	v_mov_b32_e32 v19, v129
	v_lshl_add_u64 v[4:5], v[0:1], 0, v[18:19]
	v_or_b32_e32 v206, 8, v200
	v_mov_b32_e32 v207, v201
	s_waitcnt vmcnt(8)
	v_and_b32_e32 v3, 0xffff0000, v130
	v_lshlrev_b32_e32 v2, 16, v130
	v_pk_mul_f32 v[2:3], v[2:3], s[30:31] op_sel_hi:[1,0]
	s_nop 0
	v_cvt_pk_bf16_f32 v6, v2, v3
	v_and_b32_e32 v3, 0xffff0000, v131
	v_lshlrev_b32_e32 v2, 16, v131
	v_pk_mul_f32 v[2:3], v[2:3], s[30:31] op_sel_hi:[1,0]
	s_nop 0
	v_cvt_pk_bf16_f32 v7, v2, v3
	v_and_b32_e32 v3, 0xffff0000, v132
	v_lshlrev_b32_e32 v2, 16, v132
	v_pk_mul_f32 v[2:3], v[2:3], s[30:31] op_sel_hi:[1,0]
	s_nop 0
	v_cvt_pk_bf16_f32 v8, v2, v3
	v_and_b32_e32 v3, 0xffff0000, v133
	v_lshlrev_b32_e32 v2, 16, v133
	v_pk_mul_f32 v[2:3], v[2:3], s[30:31] op_sel_hi:[1,0]
	s_nop 0
	v_cvt_pk_bf16_f32 v9, v2, v3
	ds_write_b128 v22, v[6:9] offset:37440
	s_and_saveexec_b64 s[2:3], s[42:43]
	s_xor_b64 s[40:41], exec, s[2:3]
	s_cbranch_execz .LBB0_655
	v_lshlrev_b64 v[0:1], 6, v[206:207]
	v_lshl_add_u64 v[0:1], s[54:55], 0, v[0:1]
	v_and_b32_e32 v33, 0xffff0000, v134
	v_and_b32_e32 v35, 0xffff0000, v138
	v_lshlrev_b32_e32 v34, 16, v138
	v_lshlrev_b32_e32 v32, 16, v134
	v_pk_mul_f32 v[0:1], v[150:151], v[34:35]
	v_lshlrev_b32_e32 v10, 16, v139
	v_pk_fma_f32 v[0:1], v[154:155], v[32:33], v[0:1] neg_lo:[0,0,1] neg_hi:[0,0,1]
	v_pk_mul_f32 v[28:29], v[154:155], v[34:35]
	s_nop 0
	v_pk_fma_f32 v[24:25], v[150:151], v[32:33], v[28:29]
	s_nop 0
	v_cndmask_b32_e32 v1, v25, v1, vcc
	v_cndmask_b32_e32 v0, v24, v0, vcc
	v_and_b32_e32 v25, 0xffff0000, v135
	v_lshlrev_b32_e32 v24, 16, v135
	v_and_b32_e32 v11, 0xffff0000, v139
	v_pk_mul_f32 v[14:15], v[152:153], v[10:11]
	v_pk_mul_f32 v[0:1], v[0:1], s[30:31] op_sel_hi:[1,0]
	v_pk_fma_f32 v[14:15], v[156:157], v[24:25], v[14:15] neg_lo:[0,0,1] neg_hi:[0,0,1]
	v_pk_mul_f32 v[24:25], v[152:153], v[24:25]
	v_cvt_pk_bf16_f32 v0, v0, v1
	v_pk_fma_f32 v[10:11], v[156:157], v[10:11], v[24:25]
	s_nop 0
	v_cndmask_b32_e32 v11, v11, v15, vcc
	v_cndmask_b32_e32 v10, v10, v14, vcc
	v_pk_mul_f32 v[10:11], v[10:11], s[30:31] op_sel_hi:[1,0]
	v_and_b32_e32 v15, 0xffff0000, v140
	v_cvt_pk_bf16_f32 v1, v10, v11
	v_and_b32_e32 v11, 0xffff0000, v136
	v_lshlrev_b32_e32 v10, 16, v136
	v_lshlrev_b32_e32 v14, 16, v140
	v_pk_mul_f32 v[24:25], v[142:143], v[14:15]
	v_pk_mul_f32 v[6:7], v[142:143], v[10:11]
	v_pk_fma_f32 v[24:25], v[146:147], v[10:11], v[24:25] neg_lo:[0,0,1] neg_hi:[0,0,1]
	v_pk_fma_f32 v[2:3], v[146:147], v[14:15], v[6:7]
	v_lshlrev_b32_e32 v7, 16, v141
	v_cndmask_b32_e32 v3, v3, v25, vcc
	v_cndmask_b32_e32 v2, v2, v24, vcc
	v_lshlrev_b32_e32 v6, 16, v137
	v_mov_b32_e32 v10, v148
	v_mov_b32_e32 v11, v144
	v_pk_mul_f32 v[2:3], v[2:3], s[30:31] op_sel_hi:[1,0]
	v_pk_mul_f32 v[10:11], v[10:11], v[6:7]
	v_cvt_pk_bf16_f32 v2, v2, v3
	v_sub_f32_e32 v3, v10, v11
	v_mov_b32_e32 v10, v144
	v_mov_b32_e32 v11, v148
	v_pk_mul_f32 v[6:7], v[10:11], v[6:7]
	v_mov_b32_e32 v8, v149
	v_add_f32_e32 v4, v7, v6
	v_cndmask_b32_e32 v3, v4, v3, vcc
	v_and_b32_e32 v7, 0xffff0000, v141
	v_and_b32_e32 v6, 0xffff0000, v137
	v_mov_b32_e32 v4, v145
	v_mul_f32_e32 v3, 0x3e38aa3b, v3
	v_mov_b32_e32 v9, v145
	v_pk_mul_f32 v[10:11], v[8:9], v[6:7]
	v_mov_b32_e32 v5, v149
	v_pk_mul_f32 v[4:5], v[4:5], v[6:7]
	v_cvt_pk_bf16_f32 v3, v3, s0
	v_sub_f32_e32 v8, v10, v11
	v_add_f32_e32 v4, v5, v4
	v_perm_b32 v3, 0, v3, v238
	v_cndmask_b32_e32 v6, v4, v8, vcc
.LBB0_655:
	s_andn2_saveexec_b64 s[40:41], s[40:41]
	s_cbranch_execz .LBB0_657
	v_and_b32_e32 v1, 0xffff0000, v158
	v_lshlrev_b32_e32 v0, 16, v158
	v_and_b32_e32 v7, 0xffff0000, v159
	v_lshlrev_b32_e32 v6, 16, v159
	v_pk_mul_f32 v[0:1], v[0:1], s[30:31] op_sel_hi:[1,0]
	v_pk_mul_f32 v[2:3], v[6:7], s[30:31] op_sel_hi:[1,0]
	v_cvt_pk_bf16_f32 v0, v0, v1
	v_cvt_pk_bf16_f32 v1, v2, v3
	v_and_b32_e32 v3, 0xffff0000, v160
	v_lshlrev_b32_e32 v2, 16, v160
	v_pk_mul_f32 v[2:3], v[2:3], s[30:31] op_sel_hi:[1,0]
	v_and_b32_e32 v6, 0xffff0000, v161
	v_cvt_pk_bf16_f32 v2, v2, v3
	v_lshlrev_b32_e32 v3, 16, v161
	v_mul_f32_e32 v3, 0x3e38aa3b, v3
	v_cvt_pk_bf16_f32 v3, v3, s0
	v_perm_b32 v3, 0, v3, v238
.LBB0_657:
	s_or_b64 exec, exec, s[40:41]
	v_mul_f32_e32 v4, 0x3e38aa3b, v6
	v_cvt_pk_bf16_f32 v4, v4, s0
	v_perm_b32 v3, v4, v3, s12
	ds_write_b128 v22, v[0:3] offset:37376
	v_lshl_add_u64 v[0:1], v[20:21], 0, v[128:129]
	s_mov_b64 s[2:3], 0x6000
	v_lshl_add_u64 v[0:1], v[0:1], 0, s[2:3]
	v_mov_b32_e32 v19, v129
	v_lshl_add_u64 v[4:5], v[0:1], 0, v[18:19]
	v_or_b32_e32 v208, 12, v200
	v_mov_b32_e32 v209, v201
	s_waitcnt vmcnt(0)
	v_and_b32_e32 v3, 0xffff0000, v162
	v_lshlrev_b32_e32 v2, 16, v162
	v_pk_mul_f32 v[2:3], v[2:3], s[30:31] op_sel_hi:[1,0]
	s_nop 0
	v_cvt_pk_bf16_f32 v6, v2, v3
	v_and_b32_e32 v3, 0xffff0000, v163
	v_lshlrev_b32_e32 v2, 16, v163
	v_pk_mul_f32 v[2:3], v[2:3], s[30:31] op_sel_hi:[1,0]
	s_nop 0
	v_cvt_pk_bf16_f32 v7, v2, v3
	v_and_b32_e32 v3, 0xffff0000, v164
	v_lshlrev_b32_e32 v2, 16, v164
	v_pk_mul_f32 v[2:3], v[2:3], s[30:31] op_sel_hi:[1,0]
	s_nop 0
	v_cvt_pk_bf16_f32 v8, v2, v3
	v_and_b32_e32 v3, 0xffff0000, v165
	v_lshlrev_b32_e32 v2, 16, v165
	v_pk_mul_f32 v[2:3], v[2:3], s[30:31] op_sel_hi:[1,0]
	s_nop 0
	v_cvt_pk_bf16_f32 v9, v2, v3
	ds_write_b128 v22, v[6:9] offset:39744
	s_and_saveexec_b64 s[2:3], s[42:43]
	s_xor_b64 s[40:41], exec, s[2:3]
	s_cbranch_execz .LBB0_659
	v_lshlrev_b64 v[0:1], 6, v[208:209]
	v_lshl_add_u64 v[0:1], s[54:55], 0, v[0:1]
	v_and_b32_e32 v29, 0xffff0000, v166
	v_and_b32_e32 v31, 0xffff0000, v170
	v_lshlrev_b32_e32 v30, 16, v170
	v_lshlrev_b32_e32 v28, 16, v166
	v_pk_mul_f32 v[0:1], v[182:183], v[30:31]
	v_lshlrev_b32_e32 v10, 16, v171
	v_pk_fma_f32 v[0:1], v[186:187], v[28:29], v[0:1] neg_lo:[0,0,1] neg_hi:[0,0,1]
	v_pk_mul_f32 v[24:25], v[186:187], v[30:31]
	s_nop 0
	v_pk_fma_f32 v[18:19], v[182:183], v[28:29], v[24:25]
	s_nop 0
	v_cndmask_b32_e32 v1, v19, v1, vcc
	v_cndmask_b32_e32 v0, v18, v0, vcc
	v_and_b32_e32 v19, 0xffff0000, v167
	v_lshlrev_b32_e32 v18, 16, v167
	v_and_b32_e32 v11, 0xffff0000, v171
	v_pk_mul_f32 v[14:15], v[184:185], v[10:11]
	v_pk_mul_f32 v[0:1], v[0:1], s[30:31] op_sel_hi:[1,0]
	v_pk_fma_f32 v[14:15], v[188:189], v[18:19], v[14:15] neg_lo:[0,0,1] neg_hi:[0,0,1]
	v_pk_mul_f32 v[18:19], v[184:185], v[18:19]
	v_cvt_pk_bf16_f32 v0, v0, v1
	v_pk_fma_f32 v[10:11], v[188:189], v[10:11], v[18:19]
	s_nop 0
	v_cndmask_b32_e32 v11, v11, v15, vcc
	v_cndmask_b32_e32 v10, v10, v14, vcc
	v_pk_mul_f32 v[10:11], v[10:11], s[30:31] op_sel_hi:[1,0]
	v_and_b32_e32 v15, 0xffff0000, v172
	v_cvt_pk_bf16_f32 v1, v10, v11
	v_and_b32_e32 v11, 0xffff0000, v168
	v_lshlrev_b32_e32 v10, 16, v168
	v_lshlrev_b32_e32 v14, 16, v172
	v_pk_mul_f32 v[18:19], v[174:175], v[14:15]
	v_pk_mul_f32 v[6:7], v[174:175], v[10:11]
	v_pk_fma_f32 v[18:19], v[178:179], v[10:11], v[18:19] neg_lo:[0,0,1] neg_hi:[0,0,1]
	v_pk_fma_f32 v[2:3], v[178:179], v[14:15], v[6:7]
	v_lshlrev_b32_e32 v7, 16, v173
	v_cndmask_b32_e32 v3, v3, v19, vcc
	v_cndmask_b32_e32 v2, v2, v18, vcc
	v_lshlrev_b32_e32 v6, 16, v169
	v_mov_b32_e32 v10, v180
	v_mov_b32_e32 v11, v176
	v_pk_mul_f32 v[2:3], v[2:3], s[30:31] op_sel_hi:[1,0]
	v_pk_mul_f32 v[10:11], v[10:11], v[6:7]
	v_cvt_pk_bf16_f32 v2, v2, v3
	v_sub_f32_e32 v3, v10, v11
	v_mov_b32_e32 v10, v176
	v_mov_b32_e32 v11, v180
	v_pk_mul_f32 v[6:7], v[10:11], v[6:7]
	v_mov_b32_e32 v8, v181
	v_add_f32_e32 v4, v7, v6
	v_cndmask_b32_e32 v3, v4, v3, vcc
	v_and_b32_e32 v7, 0xffff0000, v173
	v_and_b32_e32 v6, 0xffff0000, v169
	v_mov_b32_e32 v4, v177
	v_mul_f32_e32 v3, 0x3e38aa3b, v3
	v_mov_b32_e32 v9, v177
	v_pk_mul_f32 v[10:11], v[8:9], v[6:7]
	v_mov_b32_e32 v5, v181
	v_pk_mul_f32 v[4:5], v[4:5], v[6:7]
	v_cvt_pk_bf16_f32 v3, v3, s0
	v_sub_f32_e32 v8, v10, v11
	v_add_f32_e32 v4, v5, v4
	v_perm_b32 v3, 0, v3, v238
	v_cndmask_b32_e32 v6, v4, v8, vcc
.LBB0_659:
	s_andn2_saveexec_b64 s[40:41], s[40:41]
	s_cbranch_execz .LBB0_661
	v_and_b32_e32 v1, 0xffff0000, v190
	v_lshlrev_b32_e32 v0, 16, v190
	v_and_b32_e32 v7, 0xffff0000, v191
	v_lshlrev_b32_e32 v6, 16, v191
	v_pk_mul_f32 v[0:1], v[0:1], s[30:31] op_sel_hi:[1,0]
	v_pk_mul_f32 v[2:3], v[6:7], s[30:31] op_sel_hi:[1,0]
	v_cvt_pk_bf16_f32 v0, v0, v1
	v_cvt_pk_bf16_f32 v1, v2, v3
	v_and_b32_e32 v3, 0xffff0000, v192
	v_lshlrev_b32_e32 v2, 16, v192
	v_pk_mul_f32 v[2:3], v[2:3], s[30:31] op_sel_hi:[1,0]
	v_and_b32_e32 v6, 0xffff0000, v193
	v_cvt_pk_bf16_f32 v2, v2, v3
	v_lshlrev_b32_e32 v3, 16, v193
	v_mul_f32_e32 v3, 0x3e38aa3b, v3
	v_cvt_pk_bf16_f32 v3, v3, s0
	v_perm_b32 v3, 0, v3, v238
